# v12 plus P2b LoRA epilogue: bias operands read directly from the preloaded registers (copy movs removed)
# baseline (speedup 1.0000x reference)
.LBB0_561:
	s_nop 0
	v_lshl_or_b32 v150, s48, 8, v168
	v_ashrrev_i32_e32 v151, 31, v150
	v_lshl_add_u64 v[148:149], v[150:151], 2, s[10:11]
	global_load_dwordx4 v[186:189], v[148:149], off
	global_load_dwordx4 v[190:193], v[148:149], off offset:16
	global_load_dwordx4 v[194:197], v[148:149], off offset:512
	global_load_dwordx4 v[198:201], v[148:149], off offset:528
	v_ashrrev_i32_e32 v147, 31, v146
	v_lshlrev_b64 v[160:161], 11, v[146:147]
	v_lshl_add_u64 v[160:161], s[2:3], 0, v[160:161]
	v_lshlrev_b64 v[150:151], 1, v[150:151]
	v_lshl_add_u64 v[160:161], v[160:161], 0, v[150:151]
	s_waitcnt vmcnt(0)
	v_mov_b32_e32 v152, v186
	v_mov_b32_e32 v153, v187
	v_mov_b32_e32 v154, v188
	v_mov_b32_e32 v155, v189
	v_mov_b32_e32 v156, v190
	v_mov_b32_e32 v157, v191
	v_mov_b32_e32 v158, v192
	v_mov_b32_e32 v159, v193
	v_add_f32_e32 v120, v120, v152
	v_add_f32_e32 v121, v121, v153
	v_add_f32_e32 v122, v122, v154
	v_add_f32_e32 v123, v123, v155
	v_add_f32_e32 v124, v124, v156
	v_add_f32_e32 v125, v125, v157
	v_add_f32_e32 v126, v126, v158
	v_add_f32_e32 v127, v127, v159
	v_mul_f32_e32 v120, 0xbfb8aa3b, v120
	v_mul_f32_e32 v121, 0xbfb8aa3b, v121
	v_mul_f32_e32 v122, 0xbfb8aa3b, v122
	v_mul_f32_e32 v123, 0xbfb8aa3b, v123
	v_mul_f32_e32 v124, 0xbfb8aa3b, v124
	v_mul_f32_e32 v125, 0xbfb8aa3b, v125
	v_mul_f32_e32 v126, 0xbfb8aa3b, v126
	v_mul_f32_e32 v127, 0xbfb8aa3b, v127
	v_exp_f32_e32 v120, v120
	v_exp_f32_e32 v121, v121
	v_exp_f32_e32 v122, v122
	v_exp_f32_e32 v123, v123
	v_exp_f32_e32 v124, v124
	v_exp_f32_e32 v125, v125
	v_exp_f32_e32 v126, v126
	v_exp_f32_e32 v127, v127
	v_add_f32_e32 v120, 1.0, v120
	v_add_f32_e32 v121, 1.0, v121
	v_add_f32_e32 v122, 1.0, v122
	v_add_f32_e32 v123, 1.0, v123
	v_add_f32_e32 v124, 1.0, v124
	v_add_f32_e32 v125, 1.0, v125
	v_add_f32_e32 v126, 1.0, v126
	v_add_f32_e32 v127, 1.0, v127
	v_rcp_f32_e32 v120, v120
	v_rcp_f32_e32 v121, v121
	v_rcp_f32_e32 v122, v122
	v_rcp_f32_e32 v123, v123
	v_rcp_f32_e32 v124, v124
	v_rcp_f32_e32 v125, v125
	v_rcp_f32_e32 v126, v126
	v_rcp_f32_e32 v127, v127
	v_mul_f32_e32 v120, 0xbf1b4598, v120
	v_mul_f32_e32 v121, 0xbf1b4598, v121
	v_mul_f32_e32 v122, 0xbf1b4598, v122
	v_mul_f32_e32 v123, 0xbf1b4598, v123
	v_mul_f32_e32 v124, 0xbf1b4598, v124
	v_mul_f32_e32 v125, 0xbf1b4598, v125
	v_mul_f32_e32 v126, 0xbf1b4598, v126
	v_mul_f32_e32 v127, 0xbf1b4598, v127
	v_cvt_pk_bf16_f32 v120, v120, v121
	v_cvt_pk_bf16_f32 v121, v122, v123
	v_cvt_pk_bf16_f32 v122, v124, v125
	v_cvt_pk_bf16_f32 v123, v126, v127
	global_store_dwordx4 v[160:161], v[120:123], off
	s_nop 1
	v_mov_b32_e32 v122, v196
	v_mov_b32_e32 v123, v197
	s_nop 0
	v_mov_b32_e32 v124, v198
	v_mov_b32_e32 v125, v199
	v_mov_b32_e32 v126, v200
	v_mov_b32_e32 v127, v201
	v_add_f32_e32 v117, v117, v195
	v_add_f32_e32 v112, v112, v124
	v_add_f32_e32 v113, v113, v125
	v_add_f32_e32 v118, v118, v122
	v_add_f32_e32 v114, v114, v126
	v_add_f32_e32 v119, v119, v123
	v_add_f32_e32 v115, v115, v127
	v_add_f32_e32 v116, v116, v194
	v_mul_f32_e32 v112, 0xbfb8aa3b, v112
	v_mul_f32_e32 v117, 0xbfb8aa3b, v117
	v_mul_f32_e32 v113, 0xbfb8aa3b, v113
	v_mul_f32_e32 v118, 0xbfb8aa3b, v118
	v_mul_f32_e32 v114, 0xbfb8aa3b, v114
	v_mul_f32_e32 v119, 0xbfb8aa3b, v119
	v_mul_f32_e32 v115, 0xbfb8aa3b, v115
	v_mul_f32_e32 v116, 0xbfb8aa3b, v116
	v_exp_f32_e32 v112, v112
	v_exp_f32_e32 v117, v117
	v_exp_f32_e32 v113, v113
	v_exp_f32_e32 v118, v118
	v_exp_f32_e32 v114, v114
	v_exp_f32_e32 v119, v119
	v_exp_f32_e32 v115, v115
	v_exp_f32_e32 v116, v116
	v_add_f32_e32 v112, 1.0, v112
	v_add_f32_e32 v117, 1.0, v117
	v_add_f32_e32 v113, 1.0, v113
	v_add_f32_e32 v118, 1.0, v118
	v_add_f32_e32 v114, 1.0, v114
	v_add_f32_e32 v119, 1.0, v119
	v_add_f32_e32 v115, 1.0, v115
	v_add_f32_e32 v116, 1.0, v116
	v_rcp_f32_e32 v112, v112
	v_rcp_f32_e32 v117, v117
	v_rcp_f32_e32 v113, v113
	v_rcp_f32_e32 v118, v118
	v_rcp_f32_e32 v114, v114
	v_rcp_f32_e32 v119, v119
	v_rcp_f32_e32 v115, v115
	v_rcp_f32_e32 v116, v116
	v_mul_f32_e32 v120, 0xbf1b4598, v112
	v_mul_f32_e32 v112, 0xbf1b4598, v117
	v_mul_f32_e32 v117, 0xbf1b4598, v113
	v_mul_f32_e32 v113, 0xbf1b4598, v118
	v_mul_f32_e32 v118, 0xbf1b4598, v114
	v_mul_f32_e32 v114, 0xbf1b4598, v119
	v_mul_f32_e32 v115, 0xbf1b4598, v115
	v_mul_f32_e32 v116, 0xbf1b4598, v116
	v_cvt_pk_bf16_f32 v112, v116, v112
	v_cvt_pk_bf16_f32 v113, v113, v114
	v_cvt_pk_bf16_f32 v114, v120, v117
	v_cvt_pk_bf16_f32 v115, v118, v115
	global_store_dwordx4 v[160:161], v[112:115], off offset:256
	s_nop 1
	v_mov_b32_e32 v113, v187
	v_mov_b32_e32 v114, v188
	v_mov_b32_e32 v115, v189
	s_nop 0
	v_mov_b32_e32 v116, v190
	v_mov_b32_e32 v117, v191
	v_mov_b32_e32 v118, v192
	v_mov_b32_e32 v119, v193
	v_or_b32_e32 v120, 16, v146
	v_ashrrev_i32_e32 v121, 31, v120
	v_lshlrev_b64 v[120:121], 11, v[120:121]
	v_lshl_add_u64 v[120:121], s[2:3], 0, v[120:121]
	v_lshl_add_u64 v[120:121], v[120:121], 0, v[150:151]
	v_add_f32_e32 v109, v109, v113
	v_add_f32_e32 v104, v104, v116
	v_add_f32_e32 v105, v105, v117
	v_add_f32_e32 v110, v110, v114
	v_add_f32_e32 v106, v106, v118
	v_add_f32_e32 v111, v111, v115
	v_add_f32_e32 v107, v107, v119
	v_add_f32_e32 v108, v108, v186
	v_mul_f32_e32 v104, 0xbfb8aa3b, v104
	v_mul_f32_e32 v109, 0xbfb8aa3b, v109
	v_mul_f32_e32 v105, 0xbfb8aa3b, v105
	v_mul_f32_e32 v110, 0xbfb8aa3b, v110
	v_mul_f32_e32 v106, 0xbfb8aa3b, v106
	v_mul_f32_e32 v111, 0xbfb8aa3b, v111
	v_mul_f32_e32 v107, 0xbfb8aa3b, v107
	v_mul_f32_e32 v108, 0xbfb8aa3b, v108
	v_exp_f32_e32 v104, v104
	v_exp_f32_e32 v109, v109
	v_exp_f32_e32 v105, v105
	v_exp_f32_e32 v110, v110
	v_exp_f32_e32 v106, v106
	v_exp_f32_e32 v111, v111
	v_exp_f32_e32 v107, v107
	v_exp_f32_e32 v108, v108
	v_add_f32_e32 v104, 1.0, v104
	v_add_f32_e32 v109, 1.0, v109
	v_add_f32_e32 v105, 1.0, v105
	v_add_f32_e32 v110, 1.0, v110
	v_add_f32_e32 v106, 1.0, v106
	v_add_f32_e32 v111, 1.0, v111
	v_add_f32_e32 v107, 1.0, v107
	v_add_f32_e32 v108, 1.0, v108
	v_rcp_f32_e32 v104, v104
	v_rcp_f32_e32 v109, v109
	v_rcp_f32_e32 v105, v105
	v_rcp_f32_e32 v110, v110
	v_rcp_f32_e32 v106, v106
	v_rcp_f32_e32 v111, v111
	v_rcp_f32_e32 v107, v107
	v_rcp_f32_e32 v108, v108
	v_mul_f32_e32 v112, 0xbf1b4598, v104
	v_mul_f32_e32 v104, 0xbf1b4598, v109
	v_mul_f32_e32 v109, 0xbf1b4598, v105
	v_mul_f32_e32 v105, 0xbf1b4598, v110
	v_mul_f32_e32 v110, 0xbf1b4598, v106
	v_mul_f32_e32 v106, 0xbf1b4598, v111
	v_mul_f32_e32 v107, 0xbf1b4598, v107
	v_mul_f32_e32 v108, 0xbf1b4598, v108
	v_cvt_pk_bf16_f32 v104, v108, v104
	v_cvt_pk_bf16_f32 v105, v105, v106
	v_cvt_pk_bf16_f32 v106, v112, v109
	v_cvt_pk_bf16_f32 v107, v110, v107
	global_store_dwordx4 v[120:121], v[104:107], off
	s_nop 1
	v_mov_b32_e32 v106, v196
	v_mov_b32_e32 v107, v197
	s_nop 0
	v_mov_b32_e32 v108, v198
	v_mov_b32_e32 v109, v199
	v_mov_b32_e32 v110, v200
	v_mov_b32_e32 v111, v201
	v_add_f32_e32 v101, v101, v195
	v_add_f32_e32 v96, v96, v108
	v_add_f32_e32 v97, v97, v109
	v_add_f32_e32 v102, v102, v106
	v_add_f32_e32 v98, v98, v110
	v_add_f32_e32 v103, v103, v107
	v_add_f32_e32 v99, v99, v111
	v_add_f32_e32 v100, v100, v194
	v_mul_f32_e32 v96, 0xbfb8aa3b, v96
	v_mul_f32_e32 v101, 0xbfb8aa3b, v101
	v_mul_f32_e32 v97, 0xbfb8aa3b, v97
	v_mul_f32_e32 v102, 0xbfb8aa3b, v102
	v_mul_f32_e32 v98, 0xbfb8aa3b, v98
	v_mul_f32_e32 v103, 0xbfb8aa3b, v103
	v_mul_f32_e32 v99, 0xbfb8aa3b, v99
	v_mul_f32_e32 v100, 0xbfb8aa3b, v100
	v_exp_f32_e32 v96, v96
	v_exp_f32_e32 v101, v101
	v_exp_f32_e32 v97, v97
	v_exp_f32_e32 v102, v102
	v_exp_f32_e32 v98, v98
	v_exp_f32_e32 v103, v103
	v_exp_f32_e32 v99, v99
	v_exp_f32_e32 v100, v100
	v_add_f32_e32 v96, 1.0, v96
	v_add_f32_e32 v101, 1.0, v101
	v_add_f32_e32 v97, 1.0, v97
	v_add_f32_e32 v102, 1.0, v102
	v_add_f32_e32 v98, 1.0, v98
	v_add_f32_e32 v103, 1.0, v103
	v_add_f32_e32 v99, 1.0, v99
	v_add_f32_e32 v100, 1.0, v100
	v_rcp_f32_e32 v96, v96
	v_rcp_f32_e32 v101, v101
	v_rcp_f32_e32 v97, v97
	v_rcp_f32_e32 v102, v102
	v_rcp_f32_e32 v98, v98
	v_rcp_f32_e32 v103, v103
	v_rcp_f32_e32 v99, v99
	v_rcp_f32_e32 v100, v100
	v_mul_f32_e32 v104, 0xbf1b4598, v96
	v_mul_f32_e32 v96, 0xbf1b4598, v101
	v_mul_f32_e32 v101, 0xbf1b4598, v97
	v_mul_f32_e32 v97, 0xbf1b4598, v102
	v_mul_f32_e32 v102, 0xbf1b4598, v98
	v_mul_f32_e32 v98, 0xbf1b4598, v103
	v_mul_f32_e32 v99, 0xbf1b4598, v99
	v_mul_f32_e32 v100, 0xbf1b4598, v100
	v_cvt_pk_bf16_f32 v96, v100, v96
	v_cvt_pk_bf16_f32 v97, v97, v98
	v_cvt_pk_bf16_f32 v98, v104, v101
	v_cvt_pk_bf16_f32 v99, v102, v99
	global_store_dwordx4 v[120:121], v[96:99], off offset:256
	s_nop 1
	v_mov_b32_e32 v97, v187
	v_mov_b32_e32 v98, v188
	v_mov_b32_e32 v99, v189
	s_nop 0
	v_mov_b32_e32 v100, v190
	v_mov_b32_e32 v101, v191
	v_mov_b32_e32 v102, v192
	v_mov_b32_e32 v103, v193
	v_or_b32_e32 v104, 32, v146
	v_ashrrev_i32_e32 v105, 31, v104
	v_lshlrev_b64 v[104:105], 11, v[104:105]
	v_lshl_add_u64 v[104:105], s[2:3], 0, v[104:105]
	v_lshl_add_u64 v[104:105], v[104:105], 0, v[150:151]
	v_add_f32_e32 v93, v93, v97
	v_add_f32_e32 v88, v88, v100
	v_add_f32_e32 v89, v89, v101
	v_add_f32_e32 v94, v94, v98
	v_add_f32_e32 v90, v90, v102
	v_add_f32_e32 v95, v95, v99
	v_add_f32_e32 v91, v91, v103
	v_add_f32_e32 v92, v92, v186
	v_mul_f32_e32 v88, 0xbfb8aa3b, v88
	v_mul_f32_e32 v93, 0xbfb8aa3b, v93
	v_mul_f32_e32 v89, 0xbfb8aa3b, v89
	v_mul_f32_e32 v94, 0xbfb8aa3b, v94
	v_mul_f32_e32 v90, 0xbfb8aa3b, v90
	v_mul_f32_e32 v95, 0xbfb8aa3b, v95
	v_mul_f32_e32 v91, 0xbfb8aa3b, v91
	v_mul_f32_e32 v92, 0xbfb8aa3b, v92
	v_exp_f32_e32 v88, v88
	v_exp_f32_e32 v93, v93
	v_exp_f32_e32 v89, v89
	v_exp_f32_e32 v94, v94
	v_exp_f32_e32 v90, v90
	v_exp_f32_e32 v95, v95
	v_exp_f32_e32 v91, v91
	v_exp_f32_e32 v92, v92
	v_add_f32_e32 v88, 1.0, v88
	v_add_f32_e32 v93, 1.0, v93
	v_add_f32_e32 v89, 1.0, v89
	v_add_f32_e32 v94, 1.0, v94
	v_add_f32_e32 v90, 1.0, v90
	v_add_f32_e32 v95, 1.0, v95
	v_add_f32_e32 v91, 1.0, v91
	v_add_f32_e32 v92, 1.0, v92
	v_rcp_f32_e32 v88, v88
	v_rcp_f32_e32 v93, v93
	v_rcp_f32_e32 v89, v89
	v_rcp_f32_e32 v94, v94
	v_rcp_f32_e32 v90, v90
	v_rcp_f32_e32 v95, v95
	v_rcp_f32_e32 v91, v91
	v_rcp_f32_e32 v92, v92
	v_mul_f32_e32 v96, 0xbf1b4598, v88
	v_mul_f32_e32 v88, 0xbf1b4598, v93
	v_mul_f32_e32 v93, 0xbf1b4598, v89
	v_mul_f32_e32 v89, 0xbf1b4598, v94
	v_mul_f32_e32 v94, 0xbf1b4598, v90
	v_mul_f32_e32 v90, 0xbf1b4598, v95
	v_mul_f32_e32 v91, 0xbf1b4598, v91
	v_mul_f32_e32 v92, 0xbf1b4598, v92
	v_cvt_pk_bf16_f32 v88, v92, v88
	v_cvt_pk_bf16_f32 v89, v89, v90
	v_cvt_pk_bf16_f32 v90, v96, v93
	v_cvt_pk_bf16_f32 v91, v94, v91
	global_store_dwordx4 v[104:105], v[88:91], off
	s_nop 1
	v_mov_b32_e32 v90, v196
	v_mov_b32_e32 v91, v197
	s_nop 0
	v_mov_b32_e32 v92, v198
	v_mov_b32_e32 v93, v199
	v_mov_b32_e32 v94, v200
	v_mov_b32_e32 v95, v201
	v_add_f32_e32 v85, v85, v195
	v_add_f32_e32 v80, v80, v92
	v_add_f32_e32 v81, v81, v93
	v_add_f32_e32 v86, v86, v90
	v_add_f32_e32 v82, v82, v94
	v_add_f32_e32 v87, v87, v91
	v_add_f32_e32 v83, v83, v95
	v_add_f32_e32 v84, v84, v194
	v_mul_f32_e32 v80, 0xbfb8aa3b, v80
	v_mul_f32_e32 v85, 0xbfb8aa3b, v85
	v_mul_f32_e32 v81, 0xbfb8aa3b, v81
	v_mul_f32_e32 v86, 0xbfb8aa3b, v86
	v_mul_f32_e32 v82, 0xbfb8aa3b, v82
	v_mul_f32_e32 v87, 0xbfb8aa3b, v87
	v_mul_f32_e32 v83, 0xbfb8aa3b, v83
	v_mul_f32_e32 v84, 0xbfb8aa3b, v84
	v_exp_f32_e32 v80, v80
	v_exp_f32_e32 v85, v85
	v_exp_f32_e32 v81, v81
	v_exp_f32_e32 v86, v86
	v_exp_f32_e32 v82, v82
	v_exp_f32_e32 v87, v87
	v_exp_f32_e32 v83, v83
	v_exp_f32_e32 v84, v84
	v_add_f32_e32 v80, 1.0, v80
	v_add_f32_e32 v85, 1.0, v85
	v_add_f32_e32 v81, 1.0, v81
	v_add_f32_e32 v86, 1.0, v86
	v_add_f32_e32 v82, 1.0, v82
	v_add_f32_e32 v87, 1.0, v87
	v_add_f32_e32 v83, 1.0, v83
	v_add_f32_e32 v84, 1.0, v84
	v_rcp_f32_e32 v80, v80
	v_rcp_f32_e32 v85, v85
	v_rcp_f32_e32 v81, v81
	v_rcp_f32_e32 v86, v86
	v_rcp_f32_e32 v82, v82
	v_rcp_f32_e32 v87, v87
	v_rcp_f32_e32 v83, v83
	v_rcp_f32_e32 v84, v84
	v_mul_f32_e32 v88, 0xbf1b4598, v80
	v_mul_f32_e32 v80, 0xbf1b4598, v85
	v_mul_f32_e32 v85, 0xbf1b4598, v81
	v_mul_f32_e32 v81, 0xbf1b4598, v86
	v_mul_f32_e32 v86, 0xbf1b4598, v82
	v_mul_f32_e32 v82, 0xbf1b4598, v87
	v_mul_f32_e32 v83, 0xbf1b4598, v83
	v_mul_f32_e32 v84, 0xbf1b4598, v84
	v_cvt_pk_bf16_f32 v80, v84, v80
	v_cvt_pk_bf16_f32 v81, v81, v82
	v_cvt_pk_bf16_f32 v82, v88, v85
	v_cvt_pk_bf16_f32 v83, v86, v83
	global_store_dwordx4 v[104:105], v[80:83], off offset:256
	s_nop 1
	v_mov_b32_e32 v81, v187
	v_mov_b32_e32 v82, v188
	v_mov_b32_e32 v83, v189
	s_nop 0
	v_mov_b32_e32 v84, v190
	v_mov_b32_e32 v85, v191
	v_mov_b32_e32 v86, v192
	v_mov_b32_e32 v87, v193
	v_or_b32_e32 v88, 48, v146
	v_ashrrev_i32_e32 v89, 31, v88
	v_lshlrev_b64 v[88:89], 11, v[88:89]
	v_lshl_add_u64 v[88:89], s[2:3], 0, v[88:89]
	v_lshl_add_u64 v[88:89], v[88:89], 0, v[150:151]
	v_add_f32_e32 v77, v77, v81
	v_add_f32_e32 v72, v72, v84
	v_add_f32_e32 v73, v73, v85
	v_add_f32_e32 v78, v78, v82
	v_add_f32_e32 v74, v74, v86
	v_add_f32_e32 v79, v79, v83
	v_add_f32_e32 v75, v75, v87
	v_add_f32_e32 v76, v76, v186
	v_mul_f32_e32 v72, 0xbfb8aa3b, v72
	v_mul_f32_e32 v77, 0xbfb8aa3b, v77
	v_mul_f32_e32 v73, 0xbfb8aa3b, v73
	v_mul_f32_e32 v78, 0xbfb8aa3b, v78
	v_mul_f32_e32 v74, 0xbfb8aa3b, v74
	v_mul_f32_e32 v79, 0xbfb8aa3b, v79
	v_mul_f32_e32 v75, 0xbfb8aa3b, v75
	v_mul_f32_e32 v76, 0xbfb8aa3b, v76
	v_exp_f32_e32 v72, v72
	v_exp_f32_e32 v77, v77
	v_exp_f32_e32 v73, v73
	v_exp_f32_e32 v78, v78
	v_exp_f32_e32 v74, v74
	v_exp_f32_e32 v79, v79
	v_exp_f32_e32 v75, v75
	v_exp_f32_e32 v76, v76
	v_add_f32_e32 v72, 1.0, v72
	v_add_f32_e32 v77, 1.0, v77
	v_add_f32_e32 v73, 1.0, v73
	v_add_f32_e32 v78, 1.0, v78
	v_add_f32_e32 v74, 1.0, v74
	v_add_f32_e32 v79, 1.0, v79
	v_add_f32_e32 v75, 1.0, v75
	v_add_f32_e32 v76, 1.0, v76
	v_rcp_f32_e32 v72, v72
	v_rcp_f32_e32 v77, v77
	v_rcp_f32_e32 v73, v73
	v_rcp_f32_e32 v78, v78
	v_rcp_f32_e32 v74, v74
	v_rcp_f32_e32 v79, v79
	v_rcp_f32_e32 v75, v75
	v_rcp_f32_e32 v76, v76
	v_mul_f32_e32 v80, 0xbf1b4598, v72
	v_mul_f32_e32 v72, 0xbf1b4598, v77
	v_mul_f32_e32 v77, 0xbf1b4598, v73
	v_mul_f32_e32 v73, 0xbf1b4598, v78
	v_mul_f32_e32 v78, 0xbf1b4598, v74
	v_mul_f32_e32 v74, 0xbf1b4598, v79
	v_mul_f32_e32 v75, 0xbf1b4598, v75
	v_mul_f32_e32 v76, 0xbf1b4598, v76
	v_cvt_pk_bf16_f32 v72, v76, v72
	v_cvt_pk_bf16_f32 v73, v73, v74
	v_cvt_pk_bf16_f32 v74, v80, v77
	v_cvt_pk_bf16_f32 v75, v78, v75
	global_store_dwordx4 v[88:89], v[72:75], off
	s_nop 1
	v_mov_b32_e32 v74, v196
	v_mov_b32_e32 v75, v197
	s_nop 0
	v_mov_b32_e32 v76, v198
	v_mov_b32_e32 v77, v199
	v_mov_b32_e32 v78, v200
	v_mov_b32_e32 v79, v201
	v_add_f32_e32 v69, v69, v195
	v_add_f32_e32 v64, v64, v76
	v_add_f32_e32 v65, v65, v77
	v_add_f32_e32 v70, v70, v74
	v_add_f32_e32 v66, v66, v78
	v_add_f32_e32 v71, v71, v75
	v_add_f32_e32 v67, v67, v79
	v_add_f32_e32 v68, v68, v194
	v_mul_f32_e32 v64, 0xbfb8aa3b, v64
	v_mul_f32_e32 v69, 0xbfb8aa3b, v69
	v_mul_f32_e32 v65, 0xbfb8aa3b, v65
	v_mul_f32_e32 v70, 0xbfb8aa3b, v70
	v_mul_f32_e32 v66, 0xbfb8aa3b, v66
	v_mul_f32_e32 v71, 0xbfb8aa3b, v71
	v_mul_f32_e32 v67, 0xbfb8aa3b, v67
	v_mul_f32_e32 v68, 0xbfb8aa3b, v68
	v_exp_f32_e32 v64, v64
	v_exp_f32_e32 v69, v69
	v_exp_f32_e32 v65, v65
	v_exp_f32_e32 v70, v70
	v_exp_f32_e32 v66, v66
	v_exp_f32_e32 v71, v71
	v_exp_f32_e32 v67, v67
	v_exp_f32_e32 v68, v68
	v_add_f32_e32 v64, 1.0, v64
	v_add_f32_e32 v69, 1.0, v69
	v_add_f32_e32 v65, 1.0, v65
	v_add_f32_e32 v70, 1.0, v70
	v_add_f32_e32 v66, 1.0, v66
	v_add_f32_e32 v71, 1.0, v71
	v_add_f32_e32 v67, 1.0, v67
	v_add_f32_e32 v68, 1.0, v68
	v_rcp_f32_e32 v64, v64
	v_rcp_f32_e32 v69, v69
	v_rcp_f32_e32 v65, v65
	v_rcp_f32_e32 v70, v70
	v_rcp_f32_e32 v66, v66
	v_rcp_f32_e32 v71, v71
	v_rcp_f32_e32 v67, v67
	v_rcp_f32_e32 v68, v68
	v_mul_f32_e32 v72, 0xbf1b4598, v64
	v_mul_f32_e32 v64, 0xbf1b4598, v69
	v_mul_f32_e32 v69, 0xbf1b4598, v65
	v_mul_f32_e32 v65, 0xbf1b4598, v70
	v_mul_f32_e32 v70, 0xbf1b4598, v66
	v_mul_f32_e32 v66, 0xbf1b4598, v71
	v_mul_f32_e32 v67, 0xbf1b4598, v67
	v_mul_f32_e32 v68, 0xbf1b4598, v68
	v_cvt_pk_bf16_f32 v64, v68, v64
	v_cvt_pk_bf16_f32 v65, v65, v66
	v_cvt_pk_bf16_f32 v66, v72, v69
	v_cvt_pk_bf16_f32 v67, v70, v67
	global_store_dwordx4 v[88:89], v[64:67], off offset:256
	s_nop 1
	v_mov_b32_e32 v65, v187
	v_mov_b32_e32 v66, v188
	v_mov_b32_e32 v67, v189
	s_nop 0
	v_mov_b32_e32 v68, v190
	v_mov_b32_e32 v69, v191
	v_mov_b32_e32 v70, v192
	v_mov_b32_e32 v71, v193
	v_add_u32_e32 v72, 0x80, v146
	v_ashrrev_i32_e32 v73, 31, v72
	v_lshlrev_b64 v[72:73], 11, v[72:73]
	v_lshl_add_u64 v[72:73], s[2:3], 0, v[72:73]
	v_lshl_add_u64 v[72:73], v[72:73], 0, v[150:151]
	v_add_f32_e32 v61, v61, v65
	v_add_f32_e32 v56, v56, v68
	v_add_f32_e32 v57, v57, v69
	v_add_f32_e32 v62, v62, v66
	v_add_f32_e32 v58, v58, v70
	v_add_f32_e32 v63, v63, v67
	v_add_f32_e32 v59, v59, v71
	v_add_f32_e32 v60, v60, v186
	v_mul_f32_e32 v56, 0xbfb8aa3b, v56
	v_mul_f32_e32 v61, 0xbfb8aa3b, v61
	v_mul_f32_e32 v57, 0xbfb8aa3b, v57
	v_mul_f32_e32 v62, 0xbfb8aa3b, v62
	v_mul_f32_e32 v58, 0xbfb8aa3b, v58
	v_mul_f32_e32 v63, 0xbfb8aa3b, v63
	v_mul_f32_e32 v59, 0xbfb8aa3b, v59
	v_mul_f32_e32 v60, 0xbfb8aa3b, v60
	v_exp_f32_e32 v56, v56
	v_exp_f32_e32 v61, v61
	v_exp_f32_e32 v57, v57
	v_exp_f32_e32 v62, v62
	v_exp_f32_e32 v58, v58
	v_exp_f32_e32 v63, v63
	v_exp_f32_e32 v59, v59
	v_exp_f32_e32 v60, v60
	v_add_f32_e32 v56, 1.0, v56
	v_add_f32_e32 v61, 1.0, v61
	v_add_f32_e32 v57, 1.0, v57
	v_add_f32_e32 v62, 1.0, v62
	v_add_f32_e32 v58, 1.0, v58
	v_add_f32_e32 v63, 1.0, v63
	v_add_f32_e32 v59, 1.0, v59
	v_add_f32_e32 v60, 1.0, v60
	v_rcp_f32_e32 v56, v56
	v_rcp_f32_e32 v61, v61
	v_rcp_f32_e32 v57, v57
	v_rcp_f32_e32 v62, v62
	v_rcp_f32_e32 v58, v58
	v_rcp_f32_e32 v63, v63
	v_rcp_f32_e32 v59, v59
	v_rcp_f32_e32 v60, v60
	v_mul_f32_e32 v64, 0xbf1b4598, v56
	v_mul_f32_e32 v56, 0xbf1b4598, v61
	v_mul_f32_e32 v61, 0xbf1b4598, v57
	v_mul_f32_e32 v57, 0xbf1b4598, v62
	v_mul_f32_e32 v62, 0xbf1b4598, v58
	v_mul_f32_e32 v58, 0xbf1b4598, v63
	v_mul_f32_e32 v59, 0xbf1b4598, v59
	v_mul_f32_e32 v60, 0xbf1b4598, v60
	v_cvt_pk_bf16_f32 v56, v60, v56
	v_cvt_pk_bf16_f32 v57, v57, v58
	v_cvt_pk_bf16_f32 v58, v64, v61
	v_cvt_pk_bf16_f32 v59, v62, v59
	global_store_dwordx4 v[72:73], v[56:59], off
	s_nop 1
	v_mov_b32_e32 v58, v196
	v_mov_b32_e32 v59, v197
	s_nop 0
	v_mov_b32_e32 v60, v198
	v_mov_b32_e32 v61, v199
	v_mov_b32_e32 v62, v200
	v_mov_b32_e32 v63, v201
	v_add_f32_e32 v53, v53, v195
	v_add_f32_e32 v48, v48, v60
	v_add_f32_e32 v49, v49, v61
	v_add_f32_e32 v54, v54, v58
	v_add_f32_e32 v50, v50, v62
	v_add_f32_e32 v55, v55, v59
	v_add_f32_e32 v51, v51, v63
	v_add_f32_e32 v52, v52, v194
	v_mul_f32_e32 v48, 0xbfb8aa3b, v48
	v_mul_f32_e32 v53, 0xbfb8aa3b, v53
	v_mul_f32_e32 v49, 0xbfb8aa3b, v49
	v_mul_f32_e32 v54, 0xbfb8aa3b, v54
	v_mul_f32_e32 v50, 0xbfb8aa3b, v50
	v_mul_f32_e32 v55, 0xbfb8aa3b, v55
	v_mul_f32_e32 v51, 0xbfb8aa3b, v51
	v_mul_f32_e32 v52, 0xbfb8aa3b, v52
	v_exp_f32_e32 v48, v48
	v_exp_f32_e32 v53, v53
	v_exp_f32_e32 v49, v49
	v_exp_f32_e32 v54, v54
	v_exp_f32_e32 v50, v50
	v_exp_f32_e32 v55, v55
	v_exp_f32_e32 v51, v51
	v_exp_f32_e32 v52, v52
	v_add_f32_e32 v48, 1.0, v48
	v_add_f32_e32 v53, 1.0, v53
	v_add_f32_e32 v49, 1.0, v49
	v_add_f32_e32 v54, 1.0, v54
	v_add_f32_e32 v50, 1.0, v50
	v_add_f32_e32 v55, 1.0, v55
	v_add_f32_e32 v51, 1.0, v51
	v_add_f32_e32 v52, 1.0, v52
	v_rcp_f32_e32 v48, v48
	v_rcp_f32_e32 v53, v53
	v_rcp_f32_e32 v49, v49
	v_rcp_f32_e32 v54, v54
	v_rcp_f32_e32 v50, v50
	v_rcp_f32_e32 v55, v55
	v_rcp_f32_e32 v51, v51
	v_rcp_f32_e32 v52, v52
	v_mul_f32_e32 v56, 0xbf1b4598, v48
	v_mul_f32_e32 v48, 0xbf1b4598, v53
	v_mul_f32_e32 v53, 0xbf1b4598, v49
	v_mul_f32_e32 v49, 0xbf1b4598, v54
	v_mul_f32_e32 v54, 0xbf1b4598, v50
	v_mul_f32_e32 v50, 0xbf1b4598, v55
	v_mul_f32_e32 v51, 0xbf1b4598, v51
	v_mul_f32_e32 v52, 0xbf1b4598, v52
	v_cvt_pk_bf16_f32 v48, v52, v48
	v_cvt_pk_bf16_f32 v49, v49, v50
	v_cvt_pk_bf16_f32 v50, v56, v53
	v_cvt_pk_bf16_f32 v51, v54, v51
	global_store_dwordx4 v[72:73], v[48:51], off offset:256
	s_nop 1
	v_mov_b32_e32 v49, v187
	v_mov_b32_e32 v50, v188
	v_mov_b32_e32 v51, v189
	s_nop 0
	v_mov_b32_e32 v52, v190
	v_mov_b32_e32 v53, v191
	v_mov_b32_e32 v54, v192
	v_mov_b32_e32 v55, v193
	v_add_u32_e32 v56, 0x90, v146
	v_ashrrev_i32_e32 v57, 31, v56
	v_lshlrev_b64 v[56:57], 11, v[56:57]
	v_lshl_add_u64 v[56:57], s[2:3], 0, v[56:57]
	v_lshl_add_u64 v[56:57], v[56:57], 0, v[150:151]
	v_add_f32_e32 v45, v45, v49
	v_add_f32_e32 v40, v40, v52
	v_add_f32_e32 v41, v41, v53
	v_add_f32_e32 v46, v46, v50
	v_add_f32_e32 v42, v42, v54
	v_add_f32_e32 v47, v47, v51
	v_add_f32_e32 v43, v43, v55
	v_add_f32_e32 v44, v44, v186
	v_mul_f32_e32 v40, 0xbfb8aa3b, v40
	v_mul_f32_e32 v45, 0xbfb8aa3b, v45
	v_mul_f32_e32 v41, 0xbfb8aa3b, v41
	v_mul_f32_e32 v46, 0xbfb8aa3b, v46
	v_mul_f32_e32 v42, 0xbfb8aa3b, v42
	v_mul_f32_e32 v47, 0xbfb8aa3b, v47
	v_mul_f32_e32 v43, 0xbfb8aa3b, v43
	v_mul_f32_e32 v44, 0xbfb8aa3b, v44
	v_exp_f32_e32 v40, v40
	v_exp_f32_e32 v45, v45
	v_exp_f32_e32 v41, v41
	v_exp_f32_e32 v46, v46
	v_exp_f32_e32 v42, v42
	v_exp_f32_e32 v47, v47
	v_exp_f32_e32 v43, v43
	v_exp_f32_e32 v44, v44
	v_add_f32_e32 v40, 1.0, v40
	v_add_f32_e32 v45, 1.0, v45
	v_add_f32_e32 v41, 1.0, v41
	v_add_f32_e32 v46, 1.0, v46
	v_add_f32_e32 v42, 1.0, v42
	v_add_f32_e32 v47, 1.0, v47
	v_add_f32_e32 v43, 1.0, v43
	v_add_f32_e32 v44, 1.0, v44
	v_rcp_f32_e32 v40, v40
	v_rcp_f32_e32 v45, v45
	v_rcp_f32_e32 v41, v41
	v_rcp_f32_e32 v46, v46
	v_rcp_f32_e32 v42, v42
	v_rcp_f32_e32 v47, v47
	v_rcp_f32_e32 v43, v43
	v_rcp_f32_e32 v44, v44
	v_mul_f32_e32 v48, 0xbf1b4598, v40
	v_mul_f32_e32 v40, 0xbf1b4598, v45
	v_mul_f32_e32 v45, 0xbf1b4598, v41
	v_mul_f32_e32 v41, 0xbf1b4598, v46
	v_mul_f32_e32 v46, 0xbf1b4598, v42
	v_mul_f32_e32 v42, 0xbf1b4598, v47
	v_mul_f32_e32 v43, 0xbf1b4598, v43
	v_mul_f32_e32 v44, 0xbf1b4598, v44
	v_cvt_pk_bf16_f32 v40, v44, v40
	v_cvt_pk_bf16_f32 v41, v41, v42
	v_cvt_pk_bf16_f32 v42, v48, v45
	v_cvt_pk_bf16_f32 v43, v46, v43
	global_store_dwordx4 v[56:57], v[40:43], off
	s_nop 1
	v_mov_b32_e32 v42, v196
	v_mov_b32_e32 v43, v197
	s_nop 0
	v_mov_b32_e32 v44, v198
	v_mov_b32_e32 v45, v199
	v_mov_b32_e32 v46, v200
	v_mov_b32_e32 v47, v201
	v_add_f32_e32 v37, v37, v195
	v_add_f32_e32 v32, v32, v44
	v_add_f32_e32 v33, v33, v45
	v_add_f32_e32 v38, v38, v42
	v_add_f32_e32 v34, v34, v46
	v_add_f32_e32 v39, v39, v43
	v_add_f32_e32 v35, v35, v47
	v_add_f32_e32 v36, v36, v194
	v_mul_f32_e32 v32, 0xbfb8aa3b, v32
	v_mul_f32_e32 v37, 0xbfb8aa3b, v37
	v_mul_f32_e32 v33, 0xbfb8aa3b, v33
	v_mul_f32_e32 v38, 0xbfb8aa3b, v38
	v_mul_f32_e32 v34, 0xbfb8aa3b, v34
	v_mul_f32_e32 v39, 0xbfb8aa3b, v39
	v_mul_f32_e32 v35, 0xbfb8aa3b, v35
	v_mul_f32_e32 v36, 0xbfb8aa3b, v36
	v_exp_f32_e32 v32, v32
	v_exp_f32_e32 v37, v37
	v_exp_f32_e32 v33, v33
	v_exp_f32_e32 v38, v38
	v_exp_f32_e32 v34, v34
	v_exp_f32_e32 v39, v39
	v_exp_f32_e32 v35, v35
	v_exp_f32_e32 v36, v36
	v_add_f32_e32 v32, 1.0, v32
	v_add_f32_e32 v37, 1.0, v37
	v_add_f32_e32 v33, 1.0, v33
	v_add_f32_e32 v38, 1.0, v38
	v_add_f32_e32 v34, 1.0, v34
	v_add_f32_e32 v39, 1.0, v39
	v_add_f32_e32 v35, 1.0, v35
	v_add_f32_e32 v36, 1.0, v36
	v_rcp_f32_e32 v32, v32
	v_rcp_f32_e32 v37, v37
	v_rcp_f32_e32 v33, v33
	v_rcp_f32_e32 v38, v38
	v_rcp_f32_e32 v34, v34
	v_rcp_f32_e32 v39, v39
	v_rcp_f32_e32 v35, v35
	v_rcp_f32_e32 v36, v36
	v_mul_f32_e32 v40, 0xbf1b4598, v32
	v_mul_f32_e32 v32, 0xbf1b4598, v37
	v_mul_f32_e32 v37, 0xbf1b4598, v33
	v_mul_f32_e32 v33, 0xbf1b4598, v38
	v_mul_f32_e32 v38, 0xbf1b4598, v34
	v_mul_f32_e32 v34, 0xbf1b4598, v39
	v_mul_f32_e32 v35, 0xbf1b4598, v35
	v_mul_f32_e32 v36, 0xbf1b4598, v36
	v_cvt_pk_bf16_f32 v32, v36, v32
	v_cvt_pk_bf16_f32 v33, v33, v34
	v_cvt_pk_bf16_f32 v34, v40, v37
	v_cvt_pk_bf16_f32 v35, v38, v35
	global_store_dwordx4 v[56:57], v[32:35], off offset:256
	s_nop 1
	v_mov_b32_e32 v33, v187
	v_mov_b32_e32 v34, v188
	v_mov_b32_e32 v35, v189
	s_nop 0
	v_mov_b32_e32 v36, v190
	v_mov_b32_e32 v37, v191
	v_mov_b32_e32 v38, v192
	v_mov_b32_e32 v39, v193
	v_add_u32_e32 v40, 0xa0, v146
	v_ashrrev_i32_e32 v41, 31, v40
	v_lshlrev_b64 v[40:41], 11, v[40:41]
	v_lshl_add_u64 v[40:41], s[2:3], 0, v[40:41]
	v_lshl_add_u64 v[40:41], v[40:41], 0, v[150:151]
	v_add_f32_e32 v29, v29, v33
	v_add_f32_e32 v24, v24, v36
	v_add_f32_e32 v25, v25, v37
	v_add_f32_e32 v30, v30, v34
	v_add_f32_e32 v26, v26, v38
	v_add_f32_e32 v31, v31, v35
	v_add_f32_e32 v27, v27, v39
	v_add_f32_e32 v28, v28, v186
	v_mul_f32_e32 v24, 0xbfb8aa3b, v24
	v_mul_f32_e32 v29, 0xbfb8aa3b, v29
	v_mul_f32_e32 v25, 0xbfb8aa3b, v25
	v_mul_f32_e32 v30, 0xbfb8aa3b, v30
	v_mul_f32_e32 v26, 0xbfb8aa3b, v26
	v_mul_f32_e32 v31, 0xbfb8aa3b, v31
	v_mul_f32_e32 v27, 0xbfb8aa3b, v27
	v_mul_f32_e32 v28, 0xbfb8aa3b, v28
	v_exp_f32_e32 v24, v24
	v_exp_f32_e32 v29, v29
	v_exp_f32_e32 v25, v25
	v_exp_f32_e32 v30, v30
	v_exp_f32_e32 v26, v26
	v_exp_f32_e32 v31, v31
	v_exp_f32_e32 v27, v27
	v_exp_f32_e32 v28, v28
	v_add_f32_e32 v24, 1.0, v24
	v_add_f32_e32 v29, 1.0, v29
	v_add_f32_e32 v25, 1.0, v25
	v_add_f32_e32 v30, 1.0, v30
	v_add_f32_e32 v26, 1.0, v26
	v_add_f32_e32 v31, 1.0, v31
	v_add_f32_e32 v27, 1.0, v27
	v_add_f32_e32 v28, 1.0, v28
	v_rcp_f32_e32 v24, v24
	v_rcp_f32_e32 v29, v29
	v_rcp_f32_e32 v25, v25
	v_rcp_f32_e32 v30, v30
	v_rcp_f32_e32 v26, v26
	v_rcp_f32_e32 v31, v31
	v_rcp_f32_e32 v27, v27
	v_rcp_f32_e32 v28, v28
	v_mul_f32_e32 v32, 0xbf1b4598, v24
	v_mul_f32_e32 v24, 0xbf1b4598, v29
	v_mul_f32_e32 v29, 0xbf1b4598, v25
	v_mul_f32_e32 v25, 0xbf1b4598, v30
	v_mul_f32_e32 v30, 0xbf1b4598, v26
	v_mul_f32_e32 v26, 0xbf1b4598, v31
	v_mul_f32_e32 v27, 0xbf1b4598, v27
	v_mul_f32_e32 v28, 0xbf1b4598, v28
	v_cvt_pk_bf16_f32 v24, v28, v24
	v_cvt_pk_bf16_f32 v25, v25, v26
	v_cvt_pk_bf16_f32 v26, v32, v29
	v_cvt_pk_bf16_f32 v27, v30, v27
	global_store_dwordx4 v[40:41], v[24:27], off
	s_nop 1
	v_mov_b32_e32 v26, v196
	v_mov_b32_e32 v27, v197
	s_nop 0
	v_mov_b32_e32 v28, v198
	v_mov_b32_e32 v29, v199
	v_mov_b32_e32 v30, v200
	v_mov_b32_e32 v31, v201
	v_add_f32_e32 v21, v21, v195
	v_add_f32_e32 v16, v16, v28
	v_add_f32_e32 v17, v17, v29
	v_add_f32_e32 v22, v22, v26
	v_add_f32_e32 v18, v18, v30
	v_add_f32_e32 v23, v23, v27
	v_add_f32_e32 v19, v19, v31
	v_add_f32_e32 v20, v20, v194
	v_mul_f32_e32 v16, 0xbfb8aa3b, v16
	v_mul_f32_e32 v21, 0xbfb8aa3b, v21
	v_mul_f32_e32 v17, 0xbfb8aa3b, v17
	v_mul_f32_e32 v22, 0xbfb8aa3b, v22
	v_mul_f32_e32 v18, 0xbfb8aa3b, v18
	v_mul_f32_e32 v23, 0xbfb8aa3b, v23
	v_mul_f32_e32 v19, 0xbfb8aa3b, v19
	v_mul_f32_e32 v20, 0xbfb8aa3b, v20
	v_exp_f32_e32 v16, v16
	v_exp_f32_e32 v21, v21
	v_exp_f32_e32 v17, v17
	v_exp_f32_e32 v22, v22
	v_exp_f32_e32 v18, v18
	v_exp_f32_e32 v23, v23
	v_exp_f32_e32 v19, v19
	v_exp_f32_e32 v20, v20
	v_add_f32_e32 v16, 1.0, v16
	v_add_f32_e32 v21, 1.0, v21
	v_add_f32_e32 v17, 1.0, v17
	v_add_f32_e32 v22, 1.0, v22
	v_add_f32_e32 v18, 1.0, v18
	v_add_f32_e32 v23, 1.0, v23
	v_add_f32_e32 v19, 1.0, v19
	v_add_f32_e32 v20, 1.0, v20
	v_rcp_f32_e32 v16, v16
	v_rcp_f32_e32 v21, v21
	v_rcp_f32_e32 v17, v17
	v_rcp_f32_e32 v22, v22
	v_rcp_f32_e32 v18, v18
	v_rcp_f32_e32 v23, v23
	v_rcp_f32_e32 v19, v19
	v_rcp_f32_e32 v20, v20
	v_mul_f32_e32 v24, 0xbf1b4598, v16
	v_mul_f32_e32 v16, 0xbf1b4598, v21
	v_mul_f32_e32 v21, 0xbf1b4598, v17
	v_mul_f32_e32 v17, 0xbf1b4598, v22
	v_mul_f32_e32 v22, 0xbf1b4598, v18
	v_mul_f32_e32 v18, 0xbf1b4598, v23
	v_mul_f32_e32 v19, 0xbf1b4598, v19
	v_mul_f32_e32 v20, 0xbf1b4598, v20
	v_cvt_pk_bf16_f32 v16, v20, v16
	v_cvt_pk_bf16_f32 v17, v17, v18
	v_cvt_pk_bf16_f32 v18, v24, v21
	v_cvt_pk_bf16_f32 v19, v22, v19
	global_store_dwordx4 v[40:41], v[16:19], off offset:256
	s_nop 1
	v_mov_b32_e32 v17, v187
	v_mov_b32_e32 v18, v188
	v_mov_b32_e32 v19, v189
	s_nop 0
	v_mov_b32_e32 v20, v190
	v_mov_b32_e32 v21, v191
	v_mov_b32_e32 v22, v192
	v_mov_b32_e32 v23, v193
	v_add_u32_e32 v24, 0xb0, v146
	v_ashrrev_i32_e32 v25, 31, v24
	v_lshlrev_b64 v[24:25], 11, v[24:25]
	v_lshl_add_u64 v[24:25], s[2:3], 0, v[24:25]
	v_lshl_add_u64 v[24:25], v[24:25], 0, v[150:151]
	v_add_f32_e32 v13, v13, v17
	v_add_f32_e32 v8, v8, v20
	v_add_f32_e32 v9, v9, v21
	v_add_f32_e32 v14, v14, v18
	v_add_f32_e32 v10, v10, v22
	v_add_f32_e32 v15, v15, v19
	v_add_f32_e32 v11, v11, v23
	v_add_f32_e32 v12, v12, v186
	v_mul_f32_e32 v8, 0xbfb8aa3b, v8
	v_mul_f32_e32 v13, 0xbfb8aa3b, v13
	v_mul_f32_e32 v9, 0xbfb8aa3b, v9
	v_mul_f32_e32 v14, 0xbfb8aa3b, v14
	v_mul_f32_e32 v10, 0xbfb8aa3b, v10
	v_mul_f32_e32 v15, 0xbfb8aa3b, v15
	v_mul_f32_e32 v11, 0xbfb8aa3b, v11
	v_mul_f32_e32 v12, 0xbfb8aa3b, v12
	v_exp_f32_e32 v8, v8
	v_exp_f32_e32 v13, v13
	v_exp_f32_e32 v9, v9
	v_exp_f32_e32 v14, v14
	v_exp_f32_e32 v10, v10
	v_exp_f32_e32 v15, v15
	v_exp_f32_e32 v11, v11
	v_exp_f32_e32 v12, v12
	v_add_f32_e32 v8, 1.0, v8
	v_add_f32_e32 v13, 1.0, v13
	v_add_f32_e32 v9, 1.0, v9
	v_add_f32_e32 v14, 1.0, v14
	v_add_f32_e32 v10, 1.0, v10
	v_add_f32_e32 v15, 1.0, v15
	v_add_f32_e32 v11, 1.0, v11
	v_add_f32_e32 v12, 1.0, v12
	v_rcp_f32_e32 v8, v8
	v_rcp_f32_e32 v13, v13
	v_rcp_f32_e32 v9, v9
	v_rcp_f32_e32 v14, v14
	v_rcp_f32_e32 v10, v10
	v_rcp_f32_e32 v15, v15
	v_rcp_f32_e32 v11, v11
	v_rcp_f32_e32 v12, v12
	v_mul_f32_e32 v16, 0xbf1b4598, v8
	v_mul_f32_e32 v8, 0xbf1b4598, v13
	v_mul_f32_e32 v13, 0xbf1b4598, v9
	v_mul_f32_e32 v9, 0xbf1b4598, v14
	v_mul_f32_e32 v14, 0xbf1b4598, v10
	v_mul_f32_e32 v10, 0xbf1b4598, v15
	v_mul_f32_e32 v11, 0xbf1b4598, v11
	v_mul_f32_e32 v12, 0xbf1b4598, v12
	v_cvt_pk_bf16_f32 v8, v12, v8
	v_cvt_pk_bf16_f32 v9, v9, v10
	v_cvt_pk_bf16_f32 v10, v16, v13
	v_cvt_pk_bf16_f32 v11, v14, v11
	global_store_dwordx4 v[24:25], v[8:11], off
	s_nop 1
	v_mov_b32_e32 v9, v195
	v_mov_b32_e32 v10, v196
	v_mov_b32_e32 v11, v197
	s_nop 0
	v_mov_b32_e32 v12, v198
	v_mov_b32_e32 v13, v199
	v_mov_b32_e32 v14, v200
	v_mov_b32_e32 v15, v201
	v_add_f32_e32 v5, v5, v9
	v_add_f32_e32 v0, v0, v12
	v_add_f32_e32 v1, v1, v13
	v_add_f32_e32 v6, v6, v10
	v_add_f32_e32 v2, v2, v14
	v_add_f32_e32 v7, v7, v11
	v_add_f32_e32 v3, v3, v15
	v_add_f32_e32 v4, v4, v194
	v_mul_f32_e32 v0, 0xbfb8aa3b, v0
	v_mul_f32_e32 v5, 0xbfb8aa3b, v5
	v_mul_f32_e32 v1, 0xbfb8aa3b, v1
	v_mul_f32_e32 v6, 0xbfb8aa3b, v6
	v_mul_f32_e32 v2, 0xbfb8aa3b, v2
	v_mul_f32_e32 v7, 0xbfb8aa3b, v7
	v_mul_f32_e32 v3, 0xbfb8aa3b, v3
	v_mul_f32_e32 v4, 0xbfb8aa3b, v4
	v_exp_f32_e32 v0, v0
	v_exp_f32_e32 v5, v5
	v_exp_f32_e32 v1, v1
	v_exp_f32_e32 v6, v6
	v_exp_f32_e32 v2, v2
	v_exp_f32_e32 v7, v7
	v_exp_f32_e32 v3, v3
	v_exp_f32_e32 v4, v4
	v_add_f32_e32 v0, 1.0, v0
	v_add_f32_e32 v5, 1.0, v5
	v_add_f32_e32 v1, 1.0, v1
	v_add_f32_e32 v6, 1.0, v6
	v_add_f32_e32 v2, 1.0, v2
	v_add_f32_e32 v7, 1.0, v7
	v_add_f32_e32 v3, 1.0, v3
	v_add_f32_e32 v4, 1.0, v4
	v_rcp_f32_e32 v0, v0
	v_rcp_f32_e32 v5, v5
	v_rcp_f32_e32 v1, v1
	v_rcp_f32_e32 v6, v6
	v_rcp_f32_e32 v2, v2
	v_rcp_f32_e32 v7, v7
	v_rcp_f32_e32 v3, v3
	v_rcp_f32_e32 v4, v4
	v_mul_f32_e32 v8, 0xbf1b4598, v0
	v_mul_f32_e32 v0, 0xbf1b4598, v5
	v_mul_f32_e32 v5, 0xbf1b4598, v1
	v_mul_f32_e32 v1, 0xbf1b4598, v6
	v_mul_f32_e32 v6, 0xbf1b4598, v2
	v_mul_f32_e32 v2, 0xbf1b4598, v7
	v_mul_f32_e32 v3, 0xbf1b4598, v3
	v_mul_f32_e32 v4, 0xbf1b4598, v4
	v_cvt_pk_bf16_f32 v0, v4, v0
	v_cvt_pk_bf16_f32 v1, v1, v2
	v_cvt_pk_bf16_f32 v2, v8, v5
	v_cvt_pk_bf16_f32 v3, v6, v3
	global_store_dwordx4 v[24:25], v[0:3], off offset:256
	s_nop 1
	s_and_b64 vcc, exec, s[8:9]
	s_mov_b64 s[8:9], -1
	s_cbranch_vccnz .LBB0_548
	s_branch .LBB0_569

.LBB0_565:
	s_andn2_b64 vcc, exec, s[26:27]
	s_cbranch_vccnz .LBB0_567
	v_add_u32_e32 v136, s28, v170
	v_lshl_add_u64 v[152:153], v[136:137], 2, s[12:13]
	global_load_dwordx4 v[186:189], v[152:153], off
	global_load_dwordx4 v[190:193], v[152:153], off offset:16
	global_load_dwordx4 v[194:197], v[152:153], off offset:512
	global_load_dwordx4 v[198:201], v[152:153], off offset:528
	v_readlane_b32 s26, v233, 24
	v_readlane_b32 s27, v233, 25
	v_lshlrev_b64 v[164:165], 11, v[164:165]
	v_lshlrev_b64 v[162:163], 11, v[162:163]
	v_lshl_add_u64 v[182:183], s[26:27], 0, v[154:155]
	v_lshlrev_b64 v[154:155], 1, v[136:137]
	v_lshl_add_u64 v[182:183], v[182:183], 0, v[154:155]
	v_lshl_add_u64 v[164:165], s[26:27], 0, v[164:165]
	v_lshl_add_u64 v[164:165], v[164:165], 0, v[154:155]
	v_lshl_add_u64 v[162:163], s[26:27], 0, v[162:163]
	v_lshlrev_b64 v[160:161], 11, v[160:161]
	v_lshl_add_u64 v[160:161], s[26:27], 0, v[160:161]
	v_lshlrev_b64 v[158:159], 11, v[158:159]
	v_lshl_add_u64 v[158:159], s[26:27], 0, v[158:159]
	v_lshlrev_b64 v[156:157], 11, v[156:157]
	v_lshl_add_u64 v[156:157], s[26:27], 0, v[156:157]
	v_lshlrev_b64 v[150:151], 11, v[150:151]
	v_lshl_add_u64 v[150:151], s[26:27], 0, v[150:151]
	v_lshl_add_u64 v[150:151], v[150:151], 0, v[154:155]
	v_lshlrev_b64 v[148:149], 11, v[148:149]
	v_lshl_add_u64 v[148:149], s[26:27], 0, v[148:149]
	s_waitcnt vmcnt(0)
	v_add_f32_e32 v136, v120, v186
	v_add_f32_e32 v147, v124, v190
	v_add_f32_e32 v174, v121, v187
	v_add_f32_e32 v175, v125, v191
	v_add_f32_e32 v176, v122, v188
	v_add_f32_e32 v178, v126, v192
	v_add_f32_e32 v177, v123, v189
	v_add_f32_e32 v179, v127, v193
	v_mul_f32_e32 v174, 0xbfb8aa3b, v174
	v_mul_f32_e32 v175, 0xbfb8aa3b, v175
	v_mul_f32_e32 v176, 0xbfb8aa3b, v176
	v_mul_f32_e32 v178, 0xbfb8aa3b, v178
	v_mul_f32_e32 v177, 0xbfb8aa3b, v177
	v_mul_f32_e32 v136, 0xbfb8aa3b, v136
	v_mul_f32_e32 v147, 0xbfb8aa3b, v147
	v_mul_f32_e32 v179, 0xbfb8aa3b, v179
	v_exp_f32_e32 v174, v174
	v_exp_f32_e32 v175, v175
	v_exp_f32_e32 v176, v176
	v_exp_f32_e32 v178, v178
	v_exp_f32_e32 v177, v177
	v_exp_f32_e32 v136, v136
	v_exp_f32_e32 v147, v147
	v_exp_f32_e32 v179, v179
	v_add_f32_e32 v174, 1.0, v174
	v_add_f32_e32 v175, 1.0, v175
	v_add_f32_e32 v176, 1.0, v176
	v_add_f32_e32 v178, 1.0, v178
	v_add_f32_e32 v177, 1.0, v177
	v_add_f32_e32 v136, 1.0, v136
	v_add_f32_e32 v147, 1.0, v147
	v_add_f32_e32 v179, 1.0, v179
	v_rcp_f32_e32 v174, v174
	v_rcp_f32_e32 v180, v175
	v_rcp_f32_e32 v175, v176
	v_rcp_f32_e32 v176, v177
	v_rcp_f32_e32 v177, v178
	v_rcp_f32_e32 v136, v136
	v_rcp_f32_e32 v147, v147
	v_rcp_f32_e32 v178, v179
	v_cvt_pk_bf16_f32 v174, v136, v174
	v_cvt_pk_bf16_f32 v175, v175, v176
	v_cvt_pk_bf16_f32 v176, v147, v180
	v_cvt_pk_bf16_f32 v177, v177, v178
	global_store_dwordx4 v[182:183], v[174:177], off
	s_nop 1
	s_nop 0
	v_add_f32_e32 v136, v116, v194
	v_add_f32_e32 v147, v112, v198
	v_add_f32_e32 v174, v117, v195
	v_add_f32_e32 v175, v113, v199
	v_add_f32_e32 v176, v118, v196
	v_add_f32_e32 v178, v114, v200
	v_add_f32_e32 v177, v119, v197
	v_add_f32_e32 v179, v115, v201
	v_mul_f32_e32 v174, 0xbfb8aa3b, v174
	v_mul_f32_e32 v175, 0xbfb8aa3b, v175
	v_mul_f32_e32 v176, 0xbfb8aa3b, v176
	v_mul_f32_e32 v178, 0xbfb8aa3b, v178
	v_mul_f32_e32 v177, 0xbfb8aa3b, v177
	v_mul_f32_e32 v136, 0xbfb8aa3b, v136
	v_mul_f32_e32 v147, 0xbfb8aa3b, v147
	v_mul_f32_e32 v179, 0xbfb8aa3b, v179
	v_exp_f32_e32 v174, v174
	v_exp_f32_e32 v175, v175
	v_exp_f32_e32 v176, v176
	v_exp_f32_e32 v178, v178
	v_exp_f32_e32 v177, v177
	v_exp_f32_e32 v136, v136
	v_exp_f32_e32 v147, v147
	v_exp_f32_e32 v179, v179
	v_add_f32_e32 v174, 1.0, v174
	v_add_f32_e32 v175, 1.0, v175
	v_add_f32_e32 v176, 1.0, v176
	v_add_f32_e32 v178, 1.0, v178
	v_add_f32_e32 v177, 1.0, v177
	v_add_f32_e32 v136, 1.0, v136
	v_add_f32_e32 v147, 1.0, v147
	v_add_f32_e32 v179, 1.0, v179
	v_rcp_f32_e32 v174, v174
	v_rcp_f32_e32 v180, v175
	v_rcp_f32_e32 v175, v176
	v_rcp_f32_e32 v176, v177
	v_rcp_f32_e32 v177, v178
	v_rcp_f32_e32 v136, v136
	v_rcp_f32_e32 v147, v147
	v_rcp_f32_e32 v178, v179
	v_cvt_pk_bf16_f32 v174, v136, v174
	v_cvt_pk_bf16_f32 v175, v175, v176
	v_cvt_pk_bf16_f32 v176, v147, v180
	v_cvt_pk_bf16_f32 v177, v177, v178
	global_store_dwordx4 v[182:183], v[174:177], off offset:256
	s_nop 1
	s_nop 0
	v_lshl_add_u64 v[182:183], v[162:163], 0, v[154:155]
	v_add_f32_e32 v136, v108, v186
	v_add_f32_e32 v147, v104, v190
	v_add_f32_e32 v174, v109, v187
	v_add_f32_e32 v175, v105, v191
	v_add_f32_e32 v176, v110, v188
	v_add_f32_e32 v178, v106, v192
	v_add_f32_e32 v177, v111, v189
	v_add_f32_e32 v179, v107, v193
	v_mul_f32_e32 v174, 0xbfb8aa3b, v174
	v_mul_f32_e32 v175, 0xbfb8aa3b, v175
	v_mul_f32_e32 v176, 0xbfb8aa3b, v176
	v_mul_f32_e32 v178, 0xbfb8aa3b, v178
	v_mul_f32_e32 v177, 0xbfb8aa3b, v177
	v_mul_f32_e32 v136, 0xbfb8aa3b, v136
	v_mul_f32_e32 v147, 0xbfb8aa3b, v147
	v_mul_f32_e32 v179, 0xbfb8aa3b, v179
	v_exp_f32_e32 v174, v174
	v_exp_f32_e32 v175, v175
	v_exp_f32_e32 v176, v176
	v_exp_f32_e32 v178, v178
	v_exp_f32_e32 v177, v177
	v_exp_f32_e32 v136, v136
	v_exp_f32_e32 v147, v147
	v_exp_f32_e32 v179, v179
	v_add_f32_e32 v174, 1.0, v174
	v_add_f32_e32 v175, 1.0, v175
	v_add_f32_e32 v176, 1.0, v176
	v_add_f32_e32 v178, 1.0, v178
	v_add_f32_e32 v177, 1.0, v177
	v_add_f32_e32 v136, 1.0, v136
	v_add_f32_e32 v147, 1.0, v147
	v_add_f32_e32 v179, 1.0, v179
	v_rcp_f32_e32 v174, v174
	v_rcp_f32_e32 v180, v175
	v_rcp_f32_e32 v175, v176
	v_rcp_f32_e32 v176, v177
	v_rcp_f32_e32 v177, v178
	v_rcp_f32_e32 v136, v136
	v_rcp_f32_e32 v147, v147
	v_rcp_f32_e32 v178, v179
	v_cvt_pk_bf16_f32 v174, v136, v174
	v_cvt_pk_bf16_f32 v175, v175, v176
	v_cvt_pk_bf16_f32 v176, v147, v180
	v_cvt_pk_bf16_f32 v177, v177, v178
	global_store_dwordx4 v[164:165], v[174:177], off
	s_nop 1
	s_nop 0
	v_add_f32_e32 v136, v100, v194
	v_add_f32_e32 v147, v96, v198
	v_add_f32_e32 v174, v101, v195
	v_add_f32_e32 v175, v97, v199
	v_add_f32_e32 v176, v102, v196
	v_add_f32_e32 v178, v98, v200
	v_add_f32_e32 v177, v103, v197
	v_add_f32_e32 v179, v99, v201
	v_mul_f32_e32 v174, 0xbfb8aa3b, v174
	v_mul_f32_e32 v175, 0xbfb8aa3b, v175
	v_mul_f32_e32 v176, 0xbfb8aa3b, v176
	v_mul_f32_e32 v178, 0xbfb8aa3b, v178
	v_mul_f32_e32 v177, 0xbfb8aa3b, v177
	v_mul_f32_e32 v136, 0xbfb8aa3b, v136
	v_mul_f32_e32 v147, 0xbfb8aa3b, v147
	v_mul_f32_e32 v179, 0xbfb8aa3b, v179
	v_exp_f32_e32 v174, v174
	v_exp_f32_e32 v175, v175
	v_exp_f32_e32 v176, v176
	v_exp_f32_e32 v178, v178
	v_exp_f32_e32 v177, v177
	v_exp_f32_e32 v136, v136
	v_exp_f32_e32 v147, v147
	v_exp_f32_e32 v179, v179
	v_add_f32_e32 v174, 1.0, v174
	v_add_f32_e32 v175, 1.0, v175
	v_add_f32_e32 v176, 1.0, v176
	v_add_f32_e32 v178, 1.0, v178
	v_add_f32_e32 v177, 1.0, v177
	v_add_f32_e32 v136, 1.0, v136
	v_add_f32_e32 v147, 1.0, v147
	v_add_f32_e32 v179, 1.0, v179
	v_rcp_f32_e32 v174, v174
	v_rcp_f32_e32 v180, v175
	v_rcp_f32_e32 v175, v176
	v_rcp_f32_e32 v176, v177
	v_rcp_f32_e32 v177, v178
	v_rcp_f32_e32 v136, v136
	v_rcp_f32_e32 v147, v147
	v_rcp_f32_e32 v178, v179
	v_cvt_pk_bf16_f32 v174, v136, v174
	v_cvt_pk_bf16_f32 v175, v175, v176
	v_cvt_pk_bf16_f32 v176, v147, v180
	v_cvt_pk_bf16_f32 v177, v177, v178
	global_store_dwordx4 v[164:165], v[174:177], off offset:256
	s_nop 1
	s_nop 0
	v_mov_b32_e32 v180, v192
	v_mov_b32_e32 v181, v193
	v_add_f32_e32 v136, v92, v186
	v_add_f32_e32 v162, v93, v187
	v_add_f32_e32 v163, v89, v191
	v_add_f32_e32 v164, v94, v188
	v_add_f32_e32 v165, v90, v180
	v_add_f32_e32 v174, v95, v189
	v_add_f32_e32 v147, v88, v190
	v_add_f32_e32 v175, v91, v181
	v_mul_f32_e32 v162, 0xbfb8aa3b, v162
	v_mul_f32_e32 v163, 0xbfb8aa3b, v163
	v_mul_f32_e32 v164, 0xbfb8aa3b, v164
	v_mul_f32_e32 v165, 0xbfb8aa3b, v165
	v_mul_f32_e32 v174, 0xbfb8aa3b, v174
	v_mul_f32_e32 v136, 0xbfb8aa3b, v136
	v_mul_f32_e32 v147, 0xbfb8aa3b, v147
	v_mul_f32_e32 v175, 0xbfb8aa3b, v175
	v_exp_f32_e32 v162, v162
	v_exp_f32_e32 v163, v163
	v_exp_f32_e32 v164, v164
	v_exp_f32_e32 v165, v165
	v_exp_f32_e32 v174, v174
	v_exp_f32_e32 v136, v136
	v_exp_f32_e32 v147, v147
	v_exp_f32_e32 v175, v175
	v_add_f32_e32 v162, 1.0, v162
	v_add_f32_e32 v163, 1.0, v163
	v_add_f32_e32 v164, 1.0, v164
	v_add_f32_e32 v165, 1.0, v165
	v_add_f32_e32 v174, 1.0, v174
	v_add_f32_e32 v136, 1.0, v136
	v_add_f32_e32 v147, 1.0, v147
	v_add_f32_e32 v175, 1.0, v175
	v_rcp_f32_e32 v162, v162
	v_rcp_f32_e32 v176, v163
	v_rcp_f32_e32 v163, v164
	v_rcp_f32_e32 v164, v174
	v_rcp_f32_e32 v165, v165
	v_rcp_f32_e32 v136, v136
	v_rcp_f32_e32 v147, v147
	v_rcp_f32_e32 v174, v175
	v_cvt_pk_bf16_f32 v162, v136, v162
	v_cvt_pk_bf16_f32 v163, v163, v164
	v_cvt_pk_bf16_f32 v164, v147, v176
	v_cvt_pk_bf16_f32 v165, v165, v174
	global_store_dwordx4 v[182:183], v[162:165], off
	s_nop 1
	s_nop 0
	v_lshl_add_u64 v[178:179], v[160:161], 0, v[154:155]
	v_add_f32_e32 v136, v84, v194
	v_add_f32_e32 v147, v80, v198
	v_add_f32_e32 v162, v85, v195
	v_add_f32_e32 v163, v81, v199
	v_add_f32_e32 v164, v86, v196
	v_add_f32_e32 v174, v82, v200
	v_add_f32_e32 v165, v87, v197
	v_add_f32_e32 v175, v83, v201
	v_mul_f32_e32 v162, 0xbfb8aa3b, v162
	v_mul_f32_e32 v163, 0xbfb8aa3b, v163
	v_mul_f32_e32 v164, 0xbfb8aa3b, v164
	v_mul_f32_e32 v174, 0xbfb8aa3b, v174
	v_mul_f32_e32 v165, 0xbfb8aa3b, v165
	v_mul_f32_e32 v136, 0xbfb8aa3b, v136
	v_mul_f32_e32 v147, 0xbfb8aa3b, v147
	v_mul_f32_e32 v175, 0xbfb8aa3b, v175
	v_exp_f32_e32 v162, v162
	v_exp_f32_e32 v163, v163
	v_exp_f32_e32 v164, v164
	v_exp_f32_e32 v174, v174
	v_exp_f32_e32 v165, v165
	v_exp_f32_e32 v136, v136
	v_exp_f32_e32 v147, v147
	v_exp_f32_e32 v175, v175
	v_add_f32_e32 v162, 1.0, v162
	v_add_f32_e32 v163, 1.0, v163
	v_add_f32_e32 v164, 1.0, v164
	v_add_f32_e32 v174, 1.0, v174
	v_add_f32_e32 v165, 1.0, v165
	v_add_f32_e32 v136, 1.0, v136
	v_add_f32_e32 v147, 1.0, v147
	v_add_f32_e32 v175, 1.0, v175
	v_rcp_f32_e32 v162, v162
	v_rcp_f32_e32 v176, v163
	v_rcp_f32_e32 v163, v164
	v_rcp_f32_e32 v164, v165
	v_rcp_f32_e32 v165, v174
	v_rcp_f32_e32 v136, v136
	v_rcp_f32_e32 v147, v147
	v_rcp_f32_e32 v174, v175
	v_cvt_pk_bf16_f32 v162, v136, v162
	v_cvt_pk_bf16_f32 v163, v163, v164
	v_cvt_pk_bf16_f32 v164, v147, v176
	v_cvt_pk_bf16_f32 v165, v165, v174
	global_store_dwordx4 v[182:183], v[162:165], off offset:256
	s_nop 1
	s_nop 0
	v_add_f32_e32 v136, v76, v186
	v_add_f32_e32 v160, v77, v187
	v_add_f32_e32 v161, v73, v191
	v_add_f32_e32 v162, v78, v188
	v_add_f32_e32 v163, v74, v192
	v_add_f32_e32 v164, v79, v189
	v_add_f32_e32 v147, v72, v190
	v_add_f32_e32 v165, v75, v193
	v_mul_f32_e32 v160, 0xbfb8aa3b, v160
	v_mul_f32_e32 v161, 0xbfb8aa3b, v161
	v_mul_f32_e32 v162, 0xbfb8aa3b, v162
	v_mul_f32_e32 v163, 0xbfb8aa3b, v163
	v_mul_f32_e32 v164, 0xbfb8aa3b, v164
	v_mul_f32_e32 v136, 0xbfb8aa3b, v136
	v_mul_f32_e32 v147, 0xbfb8aa3b, v147
	v_mul_f32_e32 v165, 0xbfb8aa3b, v165
	v_exp_f32_e32 v160, v160
	v_exp_f32_e32 v161, v161
	v_exp_f32_e32 v162, v162
	v_exp_f32_e32 v163, v163
	v_exp_f32_e32 v164, v164
	v_exp_f32_e32 v136, v136
	v_exp_f32_e32 v147, v147
	v_exp_f32_e32 v165, v165
	v_add_f32_e32 v160, 1.0, v160
	v_add_f32_e32 v161, 1.0, v161
	v_add_f32_e32 v162, 1.0, v162
	v_add_f32_e32 v163, 1.0, v163
	v_add_f32_e32 v164, 1.0, v164
	v_add_f32_e32 v136, 1.0, v136
	v_add_f32_e32 v147, 1.0, v147
	v_add_f32_e32 v165, 1.0, v165
	v_rcp_f32_e32 v160, v160
	v_rcp_f32_e32 v174, v161
	v_rcp_f32_e32 v161, v162
	v_rcp_f32_e32 v162, v164
	v_rcp_f32_e32 v163, v163
	v_rcp_f32_e32 v136, v136
	v_rcp_f32_e32 v147, v147
	v_rcp_f32_e32 v164, v165
	v_cvt_pk_bf16_f32 v160, v136, v160
	v_cvt_pk_bf16_f32 v161, v161, v162
	v_cvt_pk_bf16_f32 v162, v147, v174
	v_cvt_pk_bf16_f32 v163, v163, v164
	global_store_dwordx4 v[178:179], v[160:163], off
	s_nop 1
	s_nop 0
	v_add_f32_e32 v136, v68, v194
	v_add_f32_e32 v160, v69, v195
	v_add_f32_e32 v161, v65, v199
	v_add_f32_e32 v162, v70, v196
	v_add_f32_e32 v164, v66, v200
	v_add_f32_e32 v163, v71, v197
	v_add_f32_e32 v147, v64, v198
	v_add_f32_e32 v165, v67, v201
	v_mul_f32_e32 v160, 0xbfb8aa3b, v160
	v_mul_f32_e32 v161, 0xbfb8aa3b, v161
	v_mul_f32_e32 v162, 0xbfb8aa3b, v162
	v_mul_f32_e32 v164, 0xbfb8aa3b, v164
	v_mul_f32_e32 v163, 0xbfb8aa3b, v163
	v_mul_f32_e32 v136, 0xbfb8aa3b, v136
	v_mul_f32_e32 v147, 0xbfb8aa3b, v147
	v_mul_f32_e32 v165, 0xbfb8aa3b, v165
	v_exp_f32_e32 v160, v160
	v_exp_f32_e32 v161, v161
	v_exp_f32_e32 v162, v162
	v_exp_f32_e32 v164, v164
	v_exp_f32_e32 v163, v163
	v_exp_f32_e32 v136, v136
	v_exp_f32_e32 v147, v147
	v_exp_f32_e32 v165, v165
	v_add_f32_e32 v160, 1.0, v160
	v_add_f32_e32 v161, 1.0, v161
	v_add_f32_e32 v162, 1.0, v162
	v_add_f32_e32 v164, 1.0, v164
	v_add_f32_e32 v163, 1.0, v163
	v_add_f32_e32 v136, 1.0, v136
	v_add_f32_e32 v147, 1.0, v147
	v_add_f32_e32 v165, 1.0, v165
	v_rcp_f32_e32 v160, v160
	v_rcp_f32_e32 v174, v161
	v_rcp_f32_e32 v161, v162
	v_rcp_f32_e32 v162, v163
	v_rcp_f32_e32 v163, v164
	v_rcp_f32_e32 v136, v136
	v_rcp_f32_e32 v147, v147
	v_rcp_f32_e32 v164, v165
	v_cvt_pk_bf16_f32 v160, v136, v160
	v_cvt_pk_bf16_f32 v161, v161, v162
	v_cvt_pk_bf16_f32 v162, v147, v174
	v_cvt_pk_bf16_f32 v163, v163, v164
	global_store_dwordx4 v[178:179], v[160:163], off offset:256
	s_nop 1
	s_nop 0
	v_mov_b32_e32 v176, v192
	v_mov_b32_e32 v177, v193
	v_lshl_add_u64 v[178:179], v[158:159], 0, v[154:155]
	v_add_f32_e32 v136, v60, v186
	v_add_f32_e32 v158, v61, v187
	v_add_f32_e32 v159, v57, v191
	v_add_f32_e32 v160, v62, v188
	v_add_f32_e32 v161, v58, v176
	v_add_f32_e32 v162, v63, v189
	v_add_f32_e32 v147, v56, v190
	v_add_f32_e32 v163, v59, v177
	v_mul_f32_e32 v158, 0xbfb8aa3b, v158
	v_mul_f32_e32 v159, 0xbfb8aa3b, v159
	v_mul_f32_e32 v160, 0xbfb8aa3b, v160
	v_mul_f32_e32 v161, 0xbfb8aa3b, v161
	v_mul_f32_e32 v162, 0xbfb8aa3b, v162
	v_mul_f32_e32 v136, 0xbfb8aa3b, v136
	v_mul_f32_e32 v147, 0xbfb8aa3b, v147
	v_mul_f32_e32 v163, 0xbfb8aa3b, v163
	v_exp_f32_e32 v158, v158
	v_exp_f32_e32 v159, v159
	v_exp_f32_e32 v160, v160
	v_exp_f32_e32 v161, v161
	v_exp_f32_e32 v162, v162
	v_exp_f32_e32 v136, v136
	v_exp_f32_e32 v147, v147
	v_exp_f32_e32 v163, v163
	v_add_f32_e32 v158, 1.0, v158
	v_add_f32_e32 v159, 1.0, v159
	v_add_f32_e32 v160, 1.0, v160
	v_add_f32_e32 v161, 1.0, v161
	v_add_f32_e32 v162, 1.0, v162
	v_add_f32_e32 v136, 1.0, v136
	v_add_f32_e32 v147, 1.0, v147
	v_add_f32_e32 v163, 1.0, v163
	v_rcp_f32_e32 v158, v158
	v_rcp_f32_e32 v164, v159
	v_rcp_f32_e32 v159, v160
	v_rcp_f32_e32 v160, v162
	v_rcp_f32_e32 v161, v161
	v_rcp_f32_e32 v136, v136
	v_rcp_f32_e32 v147, v147
	v_rcp_f32_e32 v162, v163
	v_cvt_pk_bf16_f32 v158, v136, v158
	v_cvt_pk_bf16_f32 v159, v159, v160
	v_cvt_pk_bf16_f32 v160, v147, v164
	v_cvt_pk_bf16_f32 v161, v161, v162
	global_store_dwordx4 v[178:179], v[158:161], off
	s_nop 1
	s_nop 0
	v_lshl_add_u64 v[174:175], v[156:157], 0, v[154:155]
	v_add_f32_e32 v136, v52, v194
	v_add_f32_e32 v147, v48, v198
	v_add_f32_e32 v158, v53, v195
	v_add_f32_e32 v159, v49, v199
	v_add_f32_e32 v160, v54, v196
	v_add_f32_e32 v162, v50, v200
	v_add_f32_e32 v161, v55, v197
	v_add_f32_e32 v163, v51, v201
	v_mul_f32_e32 v158, 0xbfb8aa3b, v158
	v_mul_f32_e32 v159, 0xbfb8aa3b, v159
	v_mul_f32_e32 v160, 0xbfb8aa3b, v160
	v_mul_f32_e32 v162, 0xbfb8aa3b, v162
	v_mul_f32_e32 v161, 0xbfb8aa3b, v161
	v_mul_f32_e32 v136, 0xbfb8aa3b, v136
	v_mul_f32_e32 v147, 0xbfb8aa3b, v147
	v_mul_f32_e32 v163, 0xbfb8aa3b, v163
	v_exp_f32_e32 v158, v158
	v_exp_f32_e32 v159, v159
	v_exp_f32_e32 v160, v160
	v_exp_f32_e32 v162, v162
	v_exp_f32_e32 v161, v161
	v_exp_f32_e32 v136, v136
	v_exp_f32_e32 v147, v147
	v_exp_f32_e32 v163, v163
	v_add_f32_e32 v158, 1.0, v158
	v_add_f32_e32 v159, 1.0, v159
	v_add_f32_e32 v160, 1.0, v160
	v_add_f32_e32 v162, 1.0, v162
	v_add_f32_e32 v161, 1.0, v161
	v_add_f32_e32 v136, 1.0, v136
	v_add_f32_e32 v147, 1.0, v147
	v_add_f32_e32 v163, 1.0, v163
	v_rcp_f32_e32 v158, v158
	v_rcp_f32_e32 v164, v159
	v_rcp_f32_e32 v159, v160
	v_rcp_f32_e32 v160, v161
	v_rcp_f32_e32 v161, v162
	v_rcp_f32_e32 v136, v136
	v_rcp_f32_e32 v147, v147
	v_rcp_f32_e32 v162, v163
	v_cvt_pk_bf16_f32 v158, v136, v158
	v_cvt_pk_bf16_f32 v159, v159, v160
	v_cvt_pk_bf16_f32 v160, v147, v164
	v_cvt_pk_bf16_f32 v161, v161, v162
	global_store_dwordx4 v[178:179], v[158:161], off offset:256
	s_nop 1
	s_nop 0
	v_add_f32_e32 v136, v44, v186
	v_add_f32_e32 v156, v45, v187
	v_add_f32_e32 v157, v41, v191
	v_add_f32_e32 v158, v46, v188
	v_add_f32_e32 v159, v42, v192
	v_add_f32_e32 v160, v47, v189
	v_add_f32_e32 v147, v40, v190
	v_add_f32_e32 v161, v43, v193
	v_mul_f32_e32 v156, 0xbfb8aa3b, v156
	v_mul_f32_e32 v157, 0xbfb8aa3b, v157
	v_mul_f32_e32 v158, 0xbfb8aa3b, v158
	v_mul_f32_e32 v159, 0xbfb8aa3b, v159
	v_mul_f32_e32 v160, 0xbfb8aa3b, v160
	v_mul_f32_e32 v136, 0xbfb8aa3b, v136
	v_mul_f32_e32 v147, 0xbfb8aa3b, v147
	v_mul_f32_e32 v161, 0xbfb8aa3b, v161
	v_exp_f32_e32 v156, v156
	v_exp_f32_e32 v157, v157
	v_exp_f32_e32 v158, v158
	v_exp_f32_e32 v159, v159
	v_exp_f32_e32 v160, v160
	v_exp_f32_e32 v136, v136
	v_exp_f32_e32 v147, v147
	v_exp_f32_e32 v161, v161
	v_add_f32_e32 v156, 1.0, v156
	v_add_f32_e32 v157, 1.0, v157
	v_add_f32_e32 v158, 1.0, v158
	v_add_f32_e32 v159, 1.0, v159
	v_add_f32_e32 v160, 1.0, v160
	v_add_f32_e32 v136, 1.0, v136
	v_add_f32_e32 v147, 1.0, v147
	v_add_f32_e32 v161, 1.0, v161
	v_rcp_f32_e32 v156, v156
	v_rcp_f32_e32 v162, v157
	v_rcp_f32_e32 v157, v158
	v_rcp_f32_e32 v158, v160
	v_rcp_f32_e32 v159, v159
	v_rcp_f32_e32 v136, v136
	v_rcp_f32_e32 v147, v147
	v_rcp_f32_e32 v160, v161
	v_cvt_pk_bf16_f32 v156, v136, v156
	v_cvt_pk_bf16_f32 v157, v157, v158
	v_cvt_pk_bf16_f32 v158, v147, v162
	v_cvt_pk_bf16_f32 v159, v159, v160
	global_store_dwordx4 v[174:175], v[156:159], off
	s_nop 1
	s_nop 0
	v_lshl_add_u64 v[164:165], v[148:149], 0, v[154:155]
	v_add_f32_e32 v136, v36, v194
	v_add_f32_e32 v147, v32, v198
	v_add_f32_e32 v156, v37, v195
	v_add_f32_e32 v157, v33, v199
	v_add_f32_e32 v158, v38, v196
	v_add_f32_e32 v160, v34, v200
	v_add_f32_e32 v159, v39, v197
	v_add_f32_e32 v161, v35, v201
	v_mul_f32_e32 v156, 0xbfb8aa3b, v156
	v_mul_f32_e32 v157, 0xbfb8aa3b, v157
	v_mul_f32_e32 v158, 0xbfb8aa3b, v158
	v_mul_f32_e32 v160, 0xbfb8aa3b, v160
	v_mul_f32_e32 v159, 0xbfb8aa3b, v159
	v_mul_f32_e32 v136, 0xbfb8aa3b, v136
	v_mul_f32_e32 v147, 0xbfb8aa3b, v147
	v_mul_f32_e32 v161, 0xbfb8aa3b, v161
	v_exp_f32_e32 v156, v156
	v_exp_f32_e32 v157, v157
	v_exp_f32_e32 v158, v158
	v_exp_f32_e32 v160, v160
	v_exp_f32_e32 v159, v159
	v_exp_f32_e32 v136, v136
	v_exp_f32_e32 v147, v147
	v_exp_f32_e32 v161, v161
	v_add_f32_e32 v156, 1.0, v156
	v_add_f32_e32 v157, 1.0, v157
	v_add_f32_e32 v158, 1.0, v158
	v_add_f32_e32 v160, 1.0, v160
	v_add_f32_e32 v159, 1.0, v159
	v_add_f32_e32 v136, 1.0, v136
	v_add_f32_e32 v147, 1.0, v147
	v_add_f32_e32 v161, 1.0, v161
	v_rcp_f32_e32 v156, v156
	v_rcp_f32_e32 v162, v157
	v_rcp_f32_e32 v157, v158
	v_rcp_f32_e32 v158, v159
	v_rcp_f32_e32 v159, v160
	v_rcp_f32_e32 v136, v136
	v_rcp_f32_e32 v147, v147
	v_rcp_f32_e32 v160, v161
	v_cvt_pk_bf16_f32 v156, v136, v156
	v_cvt_pk_bf16_f32 v157, v157, v158
	v_cvt_pk_bf16_f32 v158, v147, v162
	v_cvt_pk_bf16_f32 v159, v159, v160
	global_store_dwordx4 v[174:175], v[156:159], off offset:256
	s_nop 1
	s_nop 0
	v_add_f32_e32 v136, v28, v186
	v_add_f32_e32 v147, v24, v190
	v_add_f32_e32 v156, v29, v187
	v_add_f32_e32 v157, v25, v191
	v_add_f32_e32 v158, v30, v188
	v_add_f32_e32 v160, v26, v192
	v_add_f32_e32 v159, v31, v189
	v_add_f32_e32 v161, v27, v193
	v_mul_f32_e32 v156, 0xbfb8aa3b, v156
	v_mul_f32_e32 v157, 0xbfb8aa3b, v157
	v_mul_f32_e32 v158, 0xbfb8aa3b, v158
	v_mul_f32_e32 v160, 0xbfb8aa3b, v160
	v_mul_f32_e32 v159, 0xbfb8aa3b, v159
	v_mul_f32_e32 v136, 0xbfb8aa3b, v136
	v_mul_f32_e32 v147, 0xbfb8aa3b, v147
	v_mul_f32_e32 v161, 0xbfb8aa3b, v161
	v_exp_f32_e32 v156, v156
	v_exp_f32_e32 v157, v157
	v_exp_f32_e32 v158, v158
	v_exp_f32_e32 v160, v160
	v_exp_f32_e32 v159, v159
	v_exp_f32_e32 v136, v136
	v_exp_f32_e32 v147, v147
	v_exp_f32_e32 v161, v161
	v_add_f32_e32 v156, 1.0, v156
	v_add_f32_e32 v157, 1.0, v157
	v_add_f32_e32 v158, 1.0, v158
	v_add_f32_e32 v160, 1.0, v160
	v_add_f32_e32 v159, 1.0, v159
	v_add_f32_e32 v136, 1.0, v136
	v_add_f32_e32 v147, 1.0, v147
	v_add_f32_e32 v161, 1.0, v161
	v_rcp_f32_e32 v156, v156
	v_rcp_f32_e32 v162, v157
	v_rcp_f32_e32 v157, v158
	v_rcp_f32_e32 v158, v159
	v_rcp_f32_e32 v159, v160
	v_rcp_f32_e32 v136, v136
	v_rcp_f32_e32 v147, v147
	v_rcp_f32_e32 v160, v161
	v_cvt_pk_bf16_f32 v156, v136, v156
	v_cvt_pk_bf16_f32 v157, v157, v158
	v_cvt_pk_bf16_f32 v158, v147, v162
	v_cvt_pk_bf16_f32 v159, v159, v160
	global_store_dwordx4 v[150:151], v[156:159], off
	s_nop 1
	s_nop 0
	v_add_f32_e32 v136, v20, v194
	v_add_f32_e32 v147, v16, v198
	v_add_f32_e32 v156, v21, v195
	v_add_f32_e32 v157, v17, v199
	v_add_f32_e32 v158, v22, v196
	v_add_f32_e32 v160, v18, v200
	v_add_f32_e32 v159, v23, v197
	v_add_f32_e32 v161, v19, v201
	v_mul_f32_e32 v156, 0xbfb8aa3b, v156
	v_mul_f32_e32 v157, 0xbfb8aa3b, v157
	v_mul_f32_e32 v158, 0xbfb8aa3b, v158
	v_mul_f32_e32 v160, 0xbfb8aa3b, v160
	v_mul_f32_e32 v159, 0xbfb8aa3b, v159
	v_mul_f32_e32 v136, 0xbfb8aa3b, v136
	v_mul_f32_e32 v147, 0xbfb8aa3b, v147
	v_mul_f32_e32 v161, 0xbfb8aa3b, v161
	v_exp_f32_e32 v156, v156
	v_exp_f32_e32 v157, v157
	v_exp_f32_e32 v158, v158
	v_exp_f32_e32 v160, v160
	v_exp_f32_e32 v159, v159
	v_exp_f32_e32 v136, v136
	v_exp_f32_e32 v147, v147
	v_exp_f32_e32 v161, v161
	v_add_f32_e32 v156, 1.0, v156
	v_add_f32_e32 v157, 1.0, v157
	v_add_f32_e32 v158, 1.0, v158
	v_add_f32_e32 v160, 1.0, v160
	v_add_f32_e32 v159, 1.0, v159
	v_add_f32_e32 v136, 1.0, v136
	v_add_f32_e32 v147, 1.0, v147
	v_add_f32_e32 v161, 1.0, v161
	v_rcp_f32_e32 v156, v156
	v_rcp_f32_e32 v162, v157
	v_rcp_f32_e32 v157, v158
	v_rcp_f32_e32 v158, v159
	v_rcp_f32_e32 v159, v160
	v_rcp_f32_e32 v136, v136
	v_rcp_f32_e32 v147, v147
	v_rcp_f32_e32 v160, v161
	v_cvt_pk_bf16_f32 v156, v136, v156
	v_cvt_pk_bf16_f32 v157, v157, v158
	v_cvt_pk_bf16_f32 v158, v147, v162
	v_cvt_pk_bf16_f32 v159, v159, v160
	global_store_dwordx4 v[150:151], v[156:159], off offset:256
	s_nop 1
	v_mov_b32_e32 v157, v187
	v_mov_b32_e32 v158, v188
	v_mov_b32_e32 v159, v189
	s_nop 0
	v_mov_b32_e32 v160, v190
	v_mov_b32_e32 v161, v191
	v_mov_b32_e32 v162, v192
	v_mov_b32_e32 v163, v193
	v_add_f32_e32 v148, v13, v157
	v_add_f32_e32 v149, v9, v161
	v_add_f32_e32 v150, v14, v158
	v_add_f32_e32 v151, v10, v162
	v_add_f32_e32 v154, v15, v159
	v_add_f32_e32 v136, v12, v186
	v_add_f32_e32 v147, v8, v160
	v_add_f32_e32 v155, v11, v163
	v_mul_f32_e32 v148, 0xbfb8aa3b, v148
	v_mul_f32_e32 v149, 0xbfb8aa3b, v149
	v_mul_f32_e32 v150, 0xbfb8aa3b, v150
	v_mul_f32_e32 v151, 0xbfb8aa3b, v151
	v_mul_f32_e32 v154, 0xbfb8aa3b, v154
	v_mul_f32_e32 v136, 0xbfb8aa3b, v136
	v_mul_f32_e32 v147, 0xbfb8aa3b, v147
	v_mul_f32_e32 v155, 0xbfb8aa3b, v155
	v_exp_f32_e32 v148, v148
	v_exp_f32_e32 v149, v149
	v_exp_f32_e32 v150, v150
	v_exp_f32_e32 v151, v151
	v_exp_f32_e32 v154, v154
	v_exp_f32_e32 v136, v136
	v_exp_f32_e32 v147, v147
	v_exp_f32_e32 v155, v155
	v_add_f32_e32 v148, 1.0, v148
	v_add_f32_e32 v149, 1.0, v149
	v_add_f32_e32 v150, 1.0, v150
	v_add_f32_e32 v151, 1.0, v151
	v_add_f32_e32 v154, 1.0, v154
	v_add_f32_e32 v136, 1.0, v136
	v_add_f32_e32 v147, 1.0, v147
	v_add_f32_e32 v155, 1.0, v155
	v_rcp_f32_e32 v148, v148
	v_rcp_f32_e32 v156, v149
	v_rcp_f32_e32 v149, v150
	v_rcp_f32_e32 v150, v154
	v_rcp_f32_e32 v151, v151
	v_rcp_f32_e32 v136, v136
	v_rcp_f32_e32 v147, v147
	v_rcp_f32_e32 v154, v155
	v_cvt_pk_bf16_f32 v148, v136, v148
	v_cvt_pk_bf16_f32 v149, v149, v150
	v_cvt_pk_bf16_f32 v150, v147, v156
	v_cvt_pk_bf16_f32 v151, v151, v154
	global_store_dwordx4 v[164:165], v[148:151], off
	s_nop 1
	s_nop 0
	v_mov_b32_e32 v155, v201
	v_add_f32_e32 v136, v4, v194
	v_add_f32_e32 v147, v0, v198
	v_add_f32_e32 v148, v5, v195
	v_add_f32_e32 v149, v1, v199
	v_add_f32_e32 v150, v6, v196
	v_add_f32_e32 v152, v2, v200
	v_add_f32_e32 v151, v7, v197
	v_add_f32_e32 v153, v3, v155
	v_mul_f32_e32 v148, 0xbfb8aa3b, v148
	v_mul_f32_e32 v149, 0xbfb8aa3b, v149
	v_mul_f32_e32 v150, 0xbfb8aa3b, v150
	v_mul_f32_e32 v152, 0xbfb8aa3b, v152
	v_mul_f32_e32 v151, 0xbfb8aa3b, v151
	v_mul_f32_e32 v136, 0xbfb8aa3b, v136
	v_mul_f32_e32 v147, 0xbfb8aa3b, v147
	v_mul_f32_e32 v153, 0xbfb8aa3b, v153
	v_exp_f32_e32 v148, v148
	v_exp_f32_e32 v149, v149
	v_exp_f32_e32 v150, v150
	v_exp_f32_e32 v152, v152
	v_exp_f32_e32 v151, v151
	v_exp_f32_e32 v136, v136
	v_exp_f32_e32 v147, v147
	v_exp_f32_e32 v153, v153
	v_add_f32_e32 v148, 1.0, v148
	v_add_f32_e32 v149, 1.0, v149
	v_add_f32_e32 v150, 1.0, v150
	v_add_f32_e32 v152, 1.0, v152
	v_add_f32_e32 v151, 1.0, v151
	v_add_f32_e32 v136, 1.0, v136
	v_add_f32_e32 v147, 1.0, v147
	v_add_f32_e32 v153, 1.0, v153
	v_rcp_f32_e32 v148, v148
	v_rcp_f32_e32 v154, v149
	v_rcp_f32_e32 v149, v150
	v_rcp_f32_e32 v150, v151
	v_rcp_f32_e32 v151, v152
	v_rcp_f32_e32 v136, v136
	v_rcp_f32_e32 v147, v147
	v_rcp_f32_e32 v152, v153
	v_cvt_pk_bf16_f32 v148, v136, v148
	v_cvt_pk_bf16_f32 v149, v149, v150
	v_cvt_pk_bf16_f32 v150, v147, v154
	v_cvt_pk_bf16_f32 v151, v151, v152
	global_store_dwordx4 v[164:165], v[148:151], off offset:256
	s_nop 1
